# mLSTM step 4 n-update: xor-1/xor-2 lane sums via DPP instead of two ds_bpermute round trips; nvec read issued early
# baseline (speedup 1.0000x reference)
.Lmls_6:
	v_pk_mul_f32 v[184:185], v[68:69], v[236:237]
	v_pk_mul_f32 v[186:187], v[70:71], v[238:239]
	v_cvt_pk_bf16_f32 v184, v184, v185
	v_cvt_pk_bf16_f32 v186, v186, v187
	ds_write_b16 v179, v184 offset:21120
	ds_write_b16_d16_hi v179, v184 offset:21648
	ds_write_b16 v179, v186 offset:22176
	ds_write_b16_d16_hi v179, v186 offset:22704
	global_load_dwordx2 v[192:193], v[192:193], off offset:2048 sc1
	v_pk_mul_f32 v[184:185], v[72:73], v[240:241]
	v_pk_mul_f32 v[186:187], v[74:75], v[242:243]
	v_cvt_pk_bf16_f32 v184, v184, v185
	v_cvt_pk_bf16_f32 v186, v186, v187
	ds_write_b16 v179, v184 offset:25344
	ds_write_b16_d16_hi v179, v184 offset:25872
	ds_write_b16 v179, v186 offset:26400
	ds_write_b16_d16_hi v179, v186 offset:26928
	v_pk_mul_f32 v[184:185], v[76:77], v[172:173]
	v_pk_mul_f32 v[186:187], v[78:79], v[174:175]
	v_cvt_pk_bf16_f32 v184, v184, v185
	v_cvt_pk_bf16_f32 v186, v186, v187
	ds_write_b16 v179, v184 offset:29568
	ds_write_b16_d16_hi v179, v184 offset:30096
	ds_write_b16 v179, v186 offset:30624
	ds_write_b16_d16_hi v179, v186 offset:31152
	v_mad_u32_u24 v72, v215, s93, v208
	v_mad_u32_u24 v73, v216, s93, v208
	v_and_b32_e32 v74, 3, v214
	v_cmp_eq_u32_e32 vcc, 0, v74
	ds_read_b128 v[64:67], v72 offset:34816
	ds_read_b128 v[68:71], v72 offset:34848
	ds_read_b128 v[76:79], v72 offset:34880
	ds_read_b128 v[80:83], v72 offset:34912
	ds_read_b128 v[84:87], v73 offset:34816
	ds_read_b128 v[88:91], v73 offset:34848
	s_waitcnt lgkmcnt(5)
	v_mfma_f32_32x32x16_bf16 v[0:15], v[64:67], v[168:171], v[0:15]
	ds_read_b128 v[64:67], v73 offset:34880
	s_waitcnt lgkmcnt(5)
	v_mfma_f32_32x32x16_bf16 v[0:15], v[68:71], v[164:167], v[0:15]
	ds_read_b128 v[68:71], v73 offset:34912
	s_waitcnt lgkmcnt(5)
	v_mfma_f32_32x32x16_bf16 v[0:15], v[76:79], v[160:163], v[0:15]
	ds_read_b128 v[76:79], v72 offset:44032
	s_waitcnt lgkmcnt(5)
	v_mfma_f32_32x32x16_bf16 v[0:15], v[80:83], v[156:159], v[0:15]
	ds_read_b128 v[80:83], v72 offset:44064
	s_waitcnt lgkmcnt(5)
	v_mfma_f32_32x32x16_bf16 v[16:31], v[84:87], v[168:171], v[16:31]
	ds_read_b128 v[84:87], v72 offset:44096
	s_waitcnt lgkmcnt(5)
	v_mfma_f32_32x32x16_bf16 v[16:31], v[88:91], v[164:167], v[16:31]
	ds_read_b128 v[88:91], v72 offset:44128
	s_waitcnt lgkmcnt(5)
	v_mfma_f32_32x32x16_bf16 v[16:31], v[64:67], v[160:163], v[16:31]
	ds_read_b128 v[64:67], v72 offset:48640
	s_waitcnt lgkmcnt(5)
	v_mfma_f32_32x32x16_bf16 v[16:31], v[68:71], v[156:159], v[16:31]
	ds_read_b128 v[68:71], v72 offset:48672
	s_waitcnt lgkmcnt(5)
	v_mfma_f32_32x32x16_bf16 v[32:47], v[76:79], v[168:171], v[32:47]
	ds_read_b128 v[76:79], v72 offset:48704
	s_waitcnt lgkmcnt(5)
	v_mfma_f32_32x32x16_bf16 v[32:47], v[80:83], v[164:167], v[32:47]
	ds_read_b128 v[80:83], v72 offset:48736
	s_waitcnt lgkmcnt(5)
	v_mfma_f32_32x32x16_bf16 v[32:47], v[84:87], v[160:163], v[32:47]
	s_waitcnt lgkmcnt(4)
	v_mfma_f32_32x32x16_bf16 v[32:47], v[88:91], v[156:159], v[32:47]
	s_waitcnt lgkmcnt(3)
	v_mfma_f32_32x32x16_bf16 v[48:63], v[64:67], v[168:171], v[48:63]
	s_waitcnt lgkmcnt(2)
	v_mfma_f32_32x32x16_bf16 v[48:63], v[68:71], v[164:167], v[48:63]
	s_waitcnt lgkmcnt(1)
	v_mfma_f32_32x32x16_bf16 v[48:63], v[76:79], v[160:163], v[48:63]
	s_waitcnt lgkmcnt(0)
	v_mfma_f32_32x32x16_bf16 v[48:63], v[80:83], v[156:159], v[48:63]
	v_ashrrev_i32_e32 v64, 2, v214
	v_mul_lo_u32 v65, v64, s93
	v_lshlrev_b32_e32 v66, 5, v74
	v_add3_u32 v65, 0, v65, v66
	ds_read_b128 v[66:69], v65 offset:34816
	ds_read_b128 v[70:73], v65 offset:34832
	v_lshl_add_u32 v75, v64, 2, 0
	v_add_u32_e32 v75, 0x21000, v75
	ds_read_b32 v76, v75
	s_waitcnt lgkmcnt(2)
	v_lshlrev_b32_e32 v65, 16, v66
	v_and_b32_e32 v66, 0xffff0000, v66
	v_add_f32_e32 v65, v65, v66
	s_waitcnt lgkmcnt(1)
	v_lshlrev_b32_e32 v66, 16, v70
	v_and_b32_e32 v70, 0xffff0000, v70
	v_add_f32_e32 v66, v66, v70
	v_add_f32_e32 v65, v65, v66
	v_lshlrev_b32_e32 v66, 16, v67
	v_and_b32_e32 v67, 0xffff0000, v67
	v_add_f32_e32 v66, v66, v67
	v_lshlrev_b32_e32 v67, 16, v71
	v_and_b32_e32 v70, 0xffff0000, v71
	v_add_f32_e32 v67, v67, v70
	v_add_f32_e32 v65, 0, v65
	v_add_f32_e32 v66, v66, v67
	v_add_f32_e32 v65, v66, v65
	v_lshlrev_b32_e32 v66, 16, v68
	v_and_b32_e32 v67, 0xffff0000, v68
	v_add_f32_e32 v66, v66, v67
	v_lshlrev_b32_e32 v67, 16, v72
	v_and_b32_e32 v68, 0xffff0000, v72
	v_add_f32_e32 v67, v67, v68
	v_add_f32_e32 v66, v66, v67
	v_add_f32_e32 v65, v66, v65
	v_lshlrev_b32_e32 v66, 16, v69
	v_and_b32_e32 v67, 0xffff0000, v69
	v_add_f32_e32 v66, v66, v67
	v_lshlrev_b32_e32 v67, 16, v73
	v_and_b32_e32 v68, 0xffff0000, v73
	v_add_f32_e32 v67, v67, v68
	v_add_f32_e32 v66, v66, v67
	v_add_f32_e32 v65, v66, v65
	s_nop 1
	v_add_f32_dpp v65, v65, v65 quad_perm:[1,0,3,2] row_mask:0xf bank_mask:0xf
	s_nop 1
	v_add_f32_dpp v65, v65, v65 quad_perm:[2,3,0,1] row_mask:0xf bank_mask:0xf
	s_and_saveexec_b64 s[12:13], vcc
	s_cbranch_execz .LBB0_206
	s_waitcnt lgkmcnt(0)
	v_fmac_f32_e32 v65, v96, v76
	ds_write_b32 v75, v65
	s_branch .LBB0_206
